# v042: v040 + SwiGLU epilogue software-pipelined by one group (next group's packed g*u / scale ops issued under the current group's exp ops)
# baseline (speedup 1.0000x reference)
; __device__ __forceinline__ unsigned cvt_pk_bf16(float lo, float hi) { unsigned r; asm volatile("v_cvt_pk_bf16_f32 %0, %1, %2" : "=v"(r) : "v"(lo), "v"(hi)); return r; }
;     __device__ __forceinline__ void operator()(const f32x4 (&acc)[2][2][4][2], const Unit& u, int wr, int wc, int fr, int fq) const {
;     ...
;             for (int m = 0; m < 4; ++m) {
;                 float g8[8], u8[8], v[8];
; #pragma unroll
;                 for (int n = 0; n < 2; ++n)
; #pragma unroll
;                     for (int j = 0; j < 4; ++j) { g8[4 * n + j] = acc[ai][0][m][n][j]; u8[4 * n + j] = acc[ai][1][m][n][j]; }
; #pragma unroll
;                 for (int e = 0; e < 8; ++e) v[e] = __builtin_amdgcn_exp2f(-1.4426950408889634f * g8[e]);
; #pragma unroll
;                 for (int e = 0; e < 8; ++e) v[e] = __builtin_amdgcn_rcpf(1.0f + v[e]);
; #pragma unroll
;                 for (int e = 0; e < 8; ++e) v[e] = (g8[e] * u8[e]) * v[e];
;                 u32x4e w; w.x = cvt_pk_bf16(v[0], v[1]); w.y = cvt_pk_bf16(v[2], v[3]); w.z = cvt_pk_bf16(v[4], v[5]); w.w = cvt_pk_bf16(v[6], v[7]);
;                 *(u32x4e*)(H + (size_t)(row0 + ai * HALF + m * 16) * ldc + col0) = w;
.LBB0_886:
	v_mov_b32_e32 v148, 0xbfb8aa3b
	v_pk_mul_f32 v[116:117], v[124:125], v[116:117]
	v_pk_mul_f32 v[118:119], v[126:127], v[118:119]
	v_pk_mul_f32 v[120:121], v[128:129], v[120:121]
	v_pk_mul_f32 v[122:123], v[130:131], v[122:123]
	v_pk_mul_f32 v[124:125], v[124:125], v[148:149] op_sel_hi:[1,0]
	v_pk_mul_f32 v[126:127], v[126:127], v[148:149] op_sel_hi:[1,0]
	v_pk_mul_f32 v[128:129], v[128:129], v[148:149] op_sel_hi:[1,0]
	v_pk_mul_f32 v[130:131], v[130:131], v[148:149] op_sel_hi:[1,0]
	v_exp_f32_e32 v124, v124
	v_exp_f32_e32 v125, v125
	v_exp_f32_e32 v126, v126
	v_exp_f32_e32 v127, v127
	v_exp_f32_e32 v128, v128
	v_exp_f32_e32 v129, v129
	v_exp_f32_e32 v130, v130
	v_exp_f32_e32 v131, v131
	v_pk_mul_f32 v[100:101], v[108:109], v[100:101]
	v_pk_mul_f32 v[102:103], v[110:111], v[102:103]
	v_pk_mul_f32 v[104:105], v[112:113], v[104:105]
	v_pk_mul_f32 v[106:107], v[114:115], v[106:107]
	v_pk_mul_f32 v[108:109], v[108:109], v[148:149] op_sel_hi:[1,0]
	v_pk_mul_f32 v[110:111], v[110:111], v[148:149] op_sel_hi:[1,0]
	v_pk_mul_f32 v[112:113], v[112:113], v[148:149] op_sel_hi:[1,0]
	v_pk_mul_f32 v[114:115], v[114:115], v[148:149] op_sel_hi:[1,0]
	s_nop 0
	v_pk_add_f32 v[124:125], v[124:125], 1.0 op_sel_hi:[1,0]
	v_pk_add_f32 v[126:127], v[126:127], 1.0 op_sel_hi:[1,0]
	v_pk_add_f32 v[128:129], v[128:129], 1.0 op_sel_hi:[1,0]
	v_pk_add_f32 v[130:131], v[130:131], 1.0 op_sel_hi:[1,0]
	v_rcp_f32_e32 v124, v124
	v_rcp_f32_e32 v125, v125
	v_rcp_f32_e32 v126, v126
	v_rcp_f32_e32 v127, v127
	v_rcp_f32_e32 v128, v128
	v_rcp_f32_e32 v129, v129
	v_rcp_f32_e32 v130, v130
	v_rcp_f32_e32 v131, v131
	s_nop 0
	v_pk_mul_f32 v[116:117], v[124:125], v[116:117]
	v_pk_mul_f32 v[118:119], v[126:127], v[118:119]
	v_pk_mul_f32 v[120:121], v[128:129], v[120:121]
	v_pk_mul_f32 v[122:123], v[130:131], v[122:123]
	v_lshl_or_b32 v144, s30, 7, v142
	v_lshl_add_u32 v146, s31, 8, v140
	v_ashrrev_i32_e32 v145, 31, v144
	v_cvt_pk_bf16_f32 v120, v120, v121
	v_cvt_pk_bf16_f32 v121, v122, v123
	v_cvt_pk_bf16_f32 v122, v116, v117
	v_mov_b64_e32 v[116:117], s[50:51]
	v_cvt_pk_bf16_f32 v123, v118, v119
	v_lshlrev_b64 v[118:119], 1, v[144:145]
	v_mad_u32_u24 v124, v146, s44, v118
	global_store_dwordx4 v124, v[120:123], s[50:51] sc1
	v_exp_f32_e32 v108, v108
	v_exp_f32_e32 v109, v109
	v_exp_f32_e32 v110, v110
	v_exp_f32_e32 v111, v111
	v_exp_f32_e32 v112, v112
	v_exp_f32_e32 v113, v113
	v_exp_f32_e32 v114, v114
	v_exp_f32_e32 v115, v115
	v_pk_mul_f32 v[84:85], v[92:93], v[84:85]
	v_pk_mul_f32 v[86:87], v[94:95], v[86:87]
	v_pk_mul_f32 v[88:89], v[96:97], v[88:89]
	v_pk_mul_f32 v[90:91], v[98:99], v[90:91]
	v_pk_mul_f32 v[92:93], v[92:93], v[148:149] op_sel_hi:[1,0]
	v_pk_mul_f32 v[94:95], v[94:95], v[148:149] op_sel_hi:[1,0]
	v_pk_mul_f32 v[96:97], v[96:97], v[148:149] op_sel_hi:[1,0]
	v_pk_mul_f32 v[98:99], v[98:99], v[148:149] op_sel_hi:[1,0]
	s_nop 0
	v_pk_add_f32 v[108:109], v[108:109], 1.0 op_sel_hi:[1,0]
	v_pk_add_f32 v[110:111], v[110:111], 1.0 op_sel_hi:[1,0]
	v_pk_add_f32 v[112:113], v[112:113], 1.0 op_sel_hi:[1,0]
	v_pk_add_f32 v[114:115], v[114:115], 1.0 op_sel_hi:[1,0]
	v_rcp_f32_e32 v108, v108
	v_rcp_f32_e32 v109, v109
	v_rcp_f32_e32 v110, v110
	v_rcp_f32_e32 v111, v111
	v_rcp_f32_e32 v112, v112
	v_rcp_f32_e32 v113, v113
	v_rcp_f32_e32 v114, v114
	v_rcp_f32_e32 v115, v115
	s_nop 0
	v_pk_mul_f32 v[108:109], v[108:109], v[100:101]
	v_mul_f32_e32 v110, v110, v102
	v_mul_f32_e32 v103, v111, v103
	v_pk_mul_f32 v[104:105], v[112:113], v[104:105]
	v_pk_mul_f32 v[106:107], v[114:115], v[106:107]
	v_cvt_pk_bf16_f32 v100, v104, v105
	v_or_b32_e32 v104, 16, v146
	v_mad_u32_u24 v104, v104, s44, v118
	v_cvt_pk_bf16_f32 v101, v106, v107
	v_cvt_pk_bf16_f32 v102, v108, v109
	v_cvt_pk_bf16_f32 v103, v110, v103
	global_store_dwordx4 v104, v[100:103], s[50:51] sc1
	v_exp_f32_e32 v92, v92
	v_exp_f32_e32 v93, v93
	v_exp_f32_e32 v94, v94
	v_exp_f32_e32 v95, v95
	v_exp_f32_e32 v96, v96
	v_exp_f32_e32 v97, v97
	v_exp_f32_e32 v98, v98
	v_exp_f32_e32 v99, v99
	v_pk_mul_f32 v[68:69], v[76:77], v[68:69]
	v_pk_mul_f32 v[70:71], v[78:79], v[70:71]
	v_pk_mul_f32 v[72:73], v[80:81], v[72:73]
	v_pk_mul_f32 v[74:75], v[82:83], v[74:75]
	v_pk_mul_f32 v[76:77], v[76:77], v[148:149] op_sel_hi:[1,0]
	v_pk_mul_f32 v[78:79], v[78:79], v[148:149] op_sel_hi:[1,0]
	v_pk_mul_f32 v[80:81], v[80:81], v[148:149] op_sel_hi:[1,0]
	v_pk_mul_f32 v[82:83], v[82:83], v[148:149] op_sel_hi:[1,0]
	s_nop 0
	v_pk_add_f32 v[92:93], v[92:93], 1.0 op_sel_hi:[1,0]
	v_pk_add_f32 v[94:95], v[94:95], 1.0 op_sel_hi:[1,0]
	v_pk_add_f32 v[96:97], v[96:97], 1.0 op_sel_hi:[1,0]
	v_pk_add_f32 v[98:99], v[98:99], 1.0 op_sel_hi:[1,0]
	v_rcp_f32_e32 v92, v92
	v_rcp_f32_e32 v93, v93
	v_rcp_f32_e32 v94, v94
	v_rcp_f32_e32 v95, v95
	v_rcp_f32_e32 v96, v96
	v_rcp_f32_e32 v97, v97
	v_rcp_f32_e32 v98, v98
	v_rcp_f32_e32 v99, v99
	s_nop 0
	v_pk_mul_f32 v[92:93], v[92:93], v[84:85]
	v_mul_f32_e32 v94, v94, v86
	v_mul_f32_e32 v87, v95, v87
	v_pk_mul_f32 v[88:89], v[96:97], v[88:89]
	v_pk_mul_f32 v[90:91], v[98:99], v[90:91]
	v_cvt_pk_bf16_f32 v84, v88, v89
	v_or_b32_e32 v88, 32, v146
	v_mad_u32_u24 v88, v88, s44, v118
	v_cvt_pk_bf16_f32 v85, v90, v91
	v_cvt_pk_bf16_f32 v86, v92, v93
	v_cvt_pk_bf16_f32 v87, v94, v87
	global_store_dwordx4 v88, v[84:87], s[50:51] sc1
	v_exp_f32_e32 v76, v76
	v_exp_f32_e32 v77, v77
	v_exp_f32_e32 v78, v78
	v_exp_f32_e32 v79, v79
	v_exp_f32_e32 v80, v80
	v_exp_f32_e32 v81, v81
	v_exp_f32_e32 v82, v82
	v_exp_f32_e32 v83, v83
	v_pk_mul_f32 v[52:53], v[60:61], v[52:53]
	v_pk_mul_f32 v[54:55], v[62:63], v[54:55]
	v_pk_mul_f32 v[56:57], v[64:65], v[56:57]
	v_pk_mul_f32 v[58:59], v[66:67], v[58:59]
; __device__ __forceinline__ unsigned cvt_pk_bf16(float lo, float hi) { unsigned r; asm volatile("v_cvt_pk_bf16_f32 %0, %1, %2" : "=v"(r) : "v"(lo), "v"(hi)); return r; }
;     __device__ __forceinline__ void operator()(const f32x4 (&acc)[2][2][4][2], const Unit& u, int wr, int wc, int fr, int fq) const {
;     ...
;             for (int m = 0; m < 4; ++m) {
;                 float g8[8], u8[8], v[8];
; #pragma unroll
;                 for (int n = 0; n < 2; ++n)
; #pragma unroll
;                     for (int j = 0; j < 4; ++j) { g8[4 * n + j] = acc[ai][0][m][n][j]; u8[4 * n + j] = acc[ai][1][m][n][j]; }
; #pragma unroll
;                 for (int e = 0; e < 8; ++e) v[e] = __builtin_amdgcn_exp2f(-1.4426950408889634f * g8[e]);
; #pragma unroll
;                 for (int e = 0; e < 8; ++e) v[e] = __builtin_amdgcn_rcpf(1.0f + v[e]);
; #pragma unroll
;                 for (int e = 0; e < 8; ++e) v[e] = (g8[e] * u8[e]) * v[e];
;                 u32x4e w; w.x = cvt_pk_bf16(v[0], v[1]); w.y = cvt_pk_bf16(v[2], v[3]); w.z = cvt_pk_bf16(v[4], v[5]); w.w = cvt_pk_bf16(v[6], v[7]);
;                 *(u32x4e*)(H + (size_t)(row0 + ai * HALF + m * 16) * ldc + col0) = w;
	v_pk_mul_f32 v[60:61], v[60:61], v[148:149] op_sel_hi:[1,0]
	v_pk_mul_f32 v[62:63], v[62:63], v[148:149] op_sel_hi:[1,0]
	v_pk_mul_f32 v[64:65], v[64:65], v[148:149] op_sel_hi:[1,0]
	v_pk_mul_f32 v[66:67], v[66:67], v[148:149] op_sel_hi:[1,0]
	s_nop 0
	v_pk_add_f32 v[76:77], v[76:77], 1.0 op_sel_hi:[1,0]
	v_pk_add_f32 v[78:79], v[78:79], 1.0 op_sel_hi:[1,0]
	v_pk_add_f32 v[80:81], v[80:81], 1.0 op_sel_hi:[1,0]
	v_pk_add_f32 v[82:83], v[82:83], 1.0 op_sel_hi:[1,0]
	v_rcp_f32_e32 v76, v76
	v_rcp_f32_e32 v77, v77
	v_rcp_f32_e32 v78, v78
	v_rcp_f32_e32 v79, v79
	v_rcp_f32_e32 v80, v80
	v_rcp_f32_e32 v81, v81
	v_rcp_f32_e32 v82, v82
	v_rcp_f32_e32 v83, v83
	s_nop 0
	v_pk_mul_f32 v[76:77], v[76:77], v[68:69]
	v_mul_f32_e32 v78, v78, v70
	v_mul_f32_e32 v71, v79, v71
	v_pk_mul_f32 v[72:73], v[80:81], v[72:73]
	v_pk_mul_f32 v[74:75], v[82:83], v[74:75]
	v_cvt_pk_bf16_f32 v68, v72, v73
	v_or_b32_e32 v72, 48, v146
	v_mad_u32_u24 v72, v72, s44, v118
	v_cvt_pk_bf16_f32 v69, v74, v75
	v_cvt_pk_bf16_f32 v70, v76, v77
	v_cvt_pk_bf16_f32 v71, v78, v71
	global_store_dwordx4 v72, v[68:71], s[50:51] sc1
	v_exp_f32_e32 v60, v60
	v_exp_f32_e32 v61, v61
	v_exp_f32_e32 v62, v62
	v_exp_f32_e32 v63, v63
	v_exp_f32_e32 v64, v64
	v_exp_f32_e32 v65, v65
	v_exp_f32_e32 v66, v66
	v_exp_f32_e32 v67, v67
	v_pk_mul_f32 v[36:37], v[44:45], v[36:37]
	v_pk_mul_f32 v[38:39], v[46:47], v[38:39]
	v_pk_mul_f32 v[40:41], v[48:49], v[40:41]
	v_pk_mul_f32 v[42:43], v[50:51], v[42:43]
	v_pk_mul_f32 v[44:45], v[44:45], v[148:149] op_sel_hi:[1,0]
	v_pk_mul_f32 v[46:47], v[46:47], v[148:149] op_sel_hi:[1,0]
	v_pk_mul_f32 v[48:49], v[48:49], v[148:149] op_sel_hi:[1,0]
	v_pk_mul_f32 v[50:51], v[50:51], v[148:149] op_sel_hi:[1,0]
	s_nop 0
	v_pk_add_f32 v[60:61], v[60:61], 1.0 op_sel_hi:[1,0]
	v_pk_add_f32 v[62:63], v[62:63], 1.0 op_sel_hi:[1,0]
	v_pk_add_f32 v[64:65], v[64:65], 1.0 op_sel_hi:[1,0]
	v_pk_add_f32 v[66:67], v[66:67], 1.0 op_sel_hi:[1,0]
	v_rcp_f32_e32 v60, v60
	v_rcp_f32_e32 v61, v61
	v_rcp_f32_e32 v62, v62
	v_rcp_f32_e32 v63, v63
	v_rcp_f32_e32 v64, v64
	v_rcp_f32_e32 v65, v65
	v_rcp_f32_e32 v66, v66
	v_rcp_f32_e32 v67, v67
	s_nop 0
	v_pk_mul_f32 v[60:61], v[60:61], v[52:53]
	v_mul_f32_e32 v62, v62, v54
	v_mul_f32_e32 v55, v63, v55
	v_pk_mul_f32 v[56:57], v[64:65], v[56:57]
	v_pk_mul_f32 v[58:59], v[66:67], v[58:59]
	v_add_u32_e32 v68, 0x80, v146
	v_cvt_pk_bf16_f32 v52, v56, v57
	v_mad_u32_u24 v56, v68, s44, v118
	v_cvt_pk_bf16_f32 v53, v58, v59
	v_cvt_pk_bf16_f32 v54, v60, v61
	v_cvt_pk_bf16_f32 v55, v62, v55
	global_store_dwordx4 v56, v[52:55], s[50:51] sc1
	v_exp_f32_e32 v44, v44
	v_exp_f32_e32 v45, v45
	v_exp_f32_e32 v46, v46
	v_exp_f32_e32 v47, v47
	v_exp_f32_e32 v48, v48
	v_exp_f32_e32 v49, v49
	v_exp_f32_e32 v50, v50
	v_exp_f32_e32 v51, v51
	v_pk_mul_f32 v[20:21], v[28:29], v[20:21]
	v_pk_mul_f32 v[22:23], v[30:31], v[22:23]
	v_pk_mul_f32 v[24:25], v[32:33], v[24:25]
	v_pk_mul_f32 v[26:27], v[34:35], v[26:27]
	v_pk_mul_f32 v[28:29], v[28:29], v[148:149] op_sel_hi:[1,0]
	v_pk_mul_f32 v[30:31], v[30:31], v[148:149] op_sel_hi:[1,0]
	v_pk_mul_f32 v[32:33], v[32:33], v[148:149] op_sel_hi:[1,0]
	v_pk_mul_f32 v[34:35], v[34:35], v[148:149] op_sel_hi:[1,0]
	s_nop 0
	v_pk_add_f32 v[44:45], v[44:45], 1.0 op_sel_hi:[1,0]
	v_pk_add_f32 v[46:47], v[46:47], 1.0 op_sel_hi:[1,0]
	v_pk_add_f32 v[48:49], v[48:49], 1.0 op_sel_hi:[1,0]
	v_pk_add_f32 v[50:51], v[50:51], 1.0 op_sel_hi:[1,0]
	v_rcp_f32_e32 v44, v44
	v_rcp_f32_e32 v45, v45
	v_rcp_f32_e32 v46, v46
	v_rcp_f32_e32 v47, v47
	v_rcp_f32_e32 v48, v48
	v_rcp_f32_e32 v49, v49
	v_rcp_f32_e32 v50, v50
	v_rcp_f32_e32 v51, v51
	s_nop 0
	v_pk_mul_f32 v[44:45], v[44:45], v[36:37]
	v_mul_f32_e32 v46, v46, v38
	v_mul_f32_e32 v39, v47, v39
	v_pk_mul_f32 v[40:41], v[48:49], v[40:41]
	v_pk_mul_f32 v[42:43], v[50:51], v[42:43]
	v_cvt_pk_bf16_f32 v36, v40, v41
	v_add_u32_e32 v40, 0x90, v146
	v_mad_u32_u24 v40, v40, s44, v118
	v_cvt_pk_bf16_f32 v37, v42, v43
	v_cvt_pk_bf16_f32 v38, v44, v45
	v_cvt_pk_bf16_f32 v39, v46, v39
	global_store_dwordx4 v40, v[36:39], s[50:51] sc1
	v_exp_f32_e32 v28, v28
	v_exp_f32_e32 v29, v29
	v_exp_f32_e32 v30, v30
	v_exp_f32_e32 v31, v31
	v_exp_f32_e32 v32, v32
	v_exp_f32_e32 v33, v33
	v_exp_f32_e32 v34, v34
	v_exp_f32_e32 v35, v35
	v_pk_mul_f32 v[4:5], v[12:13], v[4:5]
	v_pk_mul_f32 v[6:7], v[14:15], v[6:7]
	v_pk_mul_f32 v[8:9], v[16:17], v[8:9]
	v_pk_mul_f32 v[10:11], v[18:19], v[10:11]
	v_pk_mul_f32 v[12:13], v[12:13], v[148:149] op_sel_hi:[1,0]
	v_pk_mul_f32 v[14:15], v[14:15], v[148:149] op_sel_hi:[1,0]
	v_pk_mul_f32 v[16:17], v[16:17], v[148:149] op_sel_hi:[1,0]
	v_pk_mul_f32 v[18:19], v[18:19], v[148:149] op_sel_hi:[1,0]
	s_nop 0
	v_pk_add_f32 v[28:29], v[28:29], 1.0 op_sel_hi:[1,0]
	v_pk_add_f32 v[30:31], v[30:31], 1.0 op_sel_hi:[1,0]
	v_pk_add_f32 v[32:33], v[32:33], 1.0 op_sel_hi:[1,0]
	v_pk_add_f32 v[34:35], v[34:35], 1.0 op_sel_hi:[1,0]
	v_rcp_f32_e32 v28, v28
	v_rcp_f32_e32 v29, v29
	v_rcp_f32_e32 v30, v30
	v_rcp_f32_e32 v31, v31
	v_rcp_f32_e32 v32, v32
	v_rcp_f32_e32 v33, v33
	v_rcp_f32_e32 v34, v34
	v_rcp_f32_e32 v35, v35
	s_nop 0
	v_pk_mul_f32 v[28:29], v[28:29], v[20:21]
	v_mul_f32_e32 v30, v30, v22
	v_mul_f32_e32 v23, v31, v23
	v_pk_mul_f32 v[24:25], v[32:33], v[24:25]
	v_pk_mul_f32 v[26:27], v[34:35], v[26:27]
	v_cvt_pk_bf16_f32 v20, v24, v25
	v_add_u32_e32 v24, 0xa0, v146
	v_mad_u32_u24 v24, v24, s44, v118
	v_cvt_pk_bf16_f32 v21, v26, v27
	v_cvt_pk_bf16_f32 v22, v28, v29
	v_cvt_pk_bf16_f32 v23, v30, v23
	global_store_dwordx4 v24, v[20:23], s[50:51] sc1
	v_exp_f32_e32 v12, v12
	v_exp_f32_e32 v13, v13
	v_exp_f32_e32 v14, v14
	v_exp_f32_e32 v15, v15
	v_exp_f32_e32 v16, v16
	v_exp_f32_e32 v17, v17
	v_exp_f32_e32 v18, v18
	v_exp_f32_e32 v19, v19
	s_nop 0
	v_pk_add_f32 v[12:13], v[12:13], 1.0 op_sel_hi:[1,0]
	v_pk_add_f32 v[14:15], v[14:15], 1.0 op_sel_hi:[1,0]
	v_pk_add_f32 v[16:17], v[16:17], 1.0 op_sel_hi:[1,0]
	v_pk_add_f32 v[18:19], v[18:19], 1.0 op_sel_hi:[1,0]
	v_rcp_f32_e32 v12, v12
	v_rcp_f32_e32 v13, v13
	v_rcp_f32_e32 v14, v14
	v_rcp_f32_e32 v15, v15
	v_rcp_f32_e32 v16, v16
	v_rcp_f32_e32 v17, v17
	v_rcp_f32_e32 v18, v18
	v_rcp_f32_e32 v19, v19
	s_nop 0
	v_pk_mul_f32 v[12:13], v[12:13], v[4:5]
	v_mul_f32_e32 v14, v14, v6
	v_mul_f32_e32 v7, v15, v7
	v_pk_mul_f32 v[8:9], v[16:17], v[8:9]
	v_pk_mul_f32 v[10:11], v[18:19], v[10:11]
	v_cvt_pk_bf16_f32 v4, v8, v9
	v_add_u32_e32 v8, 0xb0, v146
	v_mad_u32_u24 v8, v8, s44, v118
	s_andn2_b64 vcc, exec, s[0:1]
	s_mov_b64 s[0:1], -1
	v_cvt_pk_bf16_f32 v5, v10, v11
	v_cvt_pk_bf16_f32 v6, v12, v13
	v_cvt_pk_bf16_f32 v7, v14, v7
	global_store_dwordx4 v8, v[4:7], s[50:51] sc1
	s_cbranch_vccnz .LBB0_879
	s_andn2_b64 vcc, exec, s[4:5]
	s_cbranch_vccnz .LBB0_878
	s_barrier
	s_branch .LBB0_878
